# baseline (speedup 1.0000x reference)
; __global__ void __launch_bounds__(NT, 2) k_mega(Params p) {
;     ...
;   for (int s = 0; s < NSTEP; ++s) {
;     const int l = s / 10, q = s - l * 10;
;     const int ph = PH_INPROJ + q, c = 0;
;     run_phase(p, ph, l, c, smem);
;     if (s + 1 < NSTEP) xcd_barrier(xb, (unsigned)s);
.LBB0_156:
	v_readfirstlane_b32 s0, v160
	s_cmp_gt_u32 s12, 9
	s_cselect_b32 s1, 10, 0
	s_sub_i32 s1, s12, s1
	s_lshl_b32 s1, 1, s1
	s_and_b32 s1, s1, 10
	s_cmp_lg_u32 s1, 0
	s_cselect_b32 s1, 1, 0
	s_lshr_b32 s0, s0, 8
	s_and_b32 s1, s1, s0
	s_cmp_lg_u32 s1, 0
	s_cbranch_scc0 .Lprio_lo
	s_setprio 1
	s_branch .Lprio_done
.Lprio_lo:
	s_setprio 0
